# weight transpose: super-tiles of 4 adjacent tiles per iteration (1 KB contiguous per source row)
# speedup vs baseline: 1.0031x; 1.0011x over previous
; __device__ __forceinline__ void tr_tile(const int tid, float* tile, const float* src, int ld, int k0, int j0, bool remap, bf16_t* dst, int ldd, int kd0) {
;     const int jj = tid & 63, kq = tid >> 6;
;     const int col = remap ? win_col(j0 + jj) : (j0 + jj);
; #pragma unroll
;     for (int i = 0; i < 8; ++i) { const int kk = kq + 8 * i; tile[kk * 65 + jj] = col >= 0 ? src[(size_t)(k0 + kk) * ld + col] : 0.f; }
; __device__ __forceinline__ void conv_phase(unsigned char* lds, const Params& p, int l, const int tid) {
;     ...
;     for (int it = blockIdx.x; it < nmod + NT_IN + NT_P + NT_O; it += gridDim.x) {
;         int id = it;
;         if (id < nmod) { mod_item(tid, tile, p, id); continue; }
;         id -= nmod;
;         if (id < NT_IN) { const int kt = id & 31, jt = id >> 5; tr_tile(tid, tile, p.in[11] + (size_t)l * 2048 * IND, IND, kt * 64, jt * 64, true, (bf16_t*)(p.ws + WS_WIN), 2048, kt * 64); continue; }
;         id -= NT_IN;
;         if (id < NT_P) { const int kt = id & 31, jt = id >> 5;
;             const float* src = kt < 16 ? p.in[19] + (size_t)l * 1024 * 2048 : p.in[20] + (size_t)l * 1024 * 2048;
;             tr_tile(tid, tile, src, 2048, (kt & 15) * 64, jt * 64, false, (bf16_t*)(p.ws + WS_WP), 2048, kt * 64); continue; }
;         id -= NT_P;
;         { const int kt = id & 31, jt = id >> 5; tr_tile(tid, tile, p.in[21] + (size_t)l * 2048 * 2048, 2048, kt * 64, jt * 64, false, (bf16_t*)(p.ws + WS_WO), 2048, kt * 64); }
.LBB0_803:
	s_cmp_ge_i32 s20, s16
	s_mov_b64 s[4:5], -1
	s_cbranch_scc0 .LBB0_827
	v_readlane_b32 s50, v246, 52
	v_readlane_b32 s51, v246, 53
	v_and_b32_e32 v40, 63, v188
	v_lshrrev_b32_e32 v41, 6, v188
	v_lshrrev_b32_e32 v42, 3, v188
	v_and_b32_e32 v43, 7, v188
	v_mul_u32_u24_e32 v44, 0x41, v41
	v_add_u32_e32 v44, v44, v40
	v_lshlrev_b32_e32 v44, 2, v44
	v_mul_u32_u24_e32 v45, 0x208, v43
	v_add_u32_e32 v45, v45, v42
	v_lshlrev_b32_e32 v45, 2, v45
	v_lshlrev_b32_e32 v46, 12, v42
	v_lshl_add_u32 v46, v43, 4, v46
	v_add_u32_e32 v144, 0x0, v45
	v_add_u32_e32 v145, 0x400, v45
	v_add_u32_e32 v146, 0x4100, v45
	v_add_u32_e32 v147, 0x4500, v45
	v_add_u32_e32 v148, 0x8200, v45
	v_add_u32_e32 v149, 0x8600, v45
	v_add_u32_e32 v150, 0xc300, v45
	v_add_u32_e32 v151, 0xc700, v45
	v_readlane_b32 s21, v247, 56
	s_nop 3
	s_add_i32 s21, s21, 64
	s_sub_i32 s24, s21, s80
	s_cmp_ge_i32 s21, s80
	s_cselect_b32 s21, s24, s21
	s_cmpk_gt_i32 s21, 0x81f
	s_cbranch_scc1 .LBB0_831
.Lcv_loop:
	s_and_b32 s25, s21, 31
	s_lshr_b32 s26, s21, 5
	s_mov_b64 s[28:29], s[12:13]
	s_mov_b32 s27, 0xc040
	s_mov_b64 s[30:31], s[50:51]
	s_mov_b64 s[34:35], -1
	s_lshl_b32 s36, s25, 6
	s_mov_b32 s37, s36
	s_cmpk_gt_u32 s21, 0x61f
	s_cbranch_scc0 .Lcv_k
	s_add_i32 s37, s21, 0xfffff9e0
	s_and_b32 s25, s37, 31
	s_lshr_b32 s26, s37, 5
	s_movk_i32 s27, 0x2000
	s_mov_b64 s[34:35], 0
	s_lshl_b32 s36, s25, 6
	s_mov_b32 s37, s36
	s_cmpk_gt_u32 s21, 0x71f
	s_cbranch_scc1 .Lcv_o
	s_cmp_lt_u32 s25, 16
	s_cselect_b32 s28, s84, s86
	s_cselect_b32 s29, s85, s87
	s_add_u32 s28, s28, s2
	s_addc_u32 s29, s29, s3
	s_mov_b64 s[30:31], s[10:11]
	s_and_b32 s37, s25, 15
	s_lshl_b32 s37, s37, 6
	s_branch .Lcv_k
.Lcv_o:
	s_add_i32 s26, s26, -8
	s_mov_b64 s[28:29], s[6:7]
	s_mov_b64 s[30:31], s[8:9]
.Lcv_k:
	s_mul_i32 s40, s37, s27
	s_add_u32 s28, s28, s40
	s_addc_u32 s29, s29, 0
	s_lshl_b32 s40, s36, 1
	s_add_u32 s30, s30, s40
	s_addc_u32 s31, s31, 0
	s_lshl_b32 s41, s26, 8
	s_lshl_b32 s42, s27, 3
	s_mov_b32 s43, 0
	v_mul_lo_u32 v4, v41, s27
	v_add_u32_e32 v0, s41, v40
	v_add_u32_e32 v1, 16, v0
	v_cmp_gt_u32_e32 vcc, 0x1000, v0
	v_add_u32_e32 v2, 0xffffe000, v0
	s_nop 0
	v_cndmask_b32_e32 v1, v1, v0, vcc
	v_cmp_gt_u32_e32 vcc, 0x3000, v0
	s_nop 1
	v_cndmask_b32_e32 v1, v2, v1, vcc
	v_cmp_gt_u32_e32 vcc, 0x3010, v0
	s_nop 1
	v_cndmask_b32_e32 v1, -1, v1, vcc
	v_cndmask_b32_e64 v1, v0, v1, s[34:35]
	v_lshl_add_u32 v136, v1, 2, v4
	v_lshl_add_u64 v[2:3], s[28:29], 0, v[136:137]
	v_cmp_le_i32_e32 vcc, 0, v1
	v_mov_b32_e32 v48, 0
	v_mov_b32_e32 v49, 0
	v_mov_b32_e32 v50, 0
	v_mov_b32_e32 v51, 0
	v_mov_b32_e32 v52, 0
	v_mov_b32_e32 v53, 0
	v_mov_b32_e32 v54, 0
	v_mov_b32_e32 v55, 0
	s_and_saveexec_b64 s[44:45], vcc
	global_load_dword v48, v[2:3], off
	v_lshl_add_u64 v[2:3], v[2:3], 0, s[42:43]
	global_load_dword v49, v[2:3], off
	v_lshl_add_u64 v[2:3], v[2:3], 0, s[42:43]
	global_load_dword v50, v[2:3], off
	v_lshl_add_u64 v[2:3], v[2:3], 0, s[42:43]
	global_load_dword v51, v[2:3], off
	v_lshl_add_u64 v[2:3], v[2:3], 0, s[42:43]
	global_load_dword v52, v[2:3], off
	v_lshl_add_u64 v[2:3], v[2:3], 0, s[42:43]
	global_load_dword v53, v[2:3], off
	v_lshl_add_u64 v[2:3], v[2:3], 0, s[42:43]
	global_load_dword v54, v[2:3], off
	v_lshl_add_u64 v[2:3], v[2:3], 0, s[42:43]
	global_load_dword v55, v[2:3], off
	s_mov_b64 exec, s[44:45]
	s_lshl_b32 s40, s41, 12
	v_add_u32_e32 v136, s40, v46
	v_lshl_add_u64 v[112:113], s[30:31], 0, v[136:137]
	s_add_i32 s41, s41, 64
	v_add_u32_e32 v0, s41, v40
	v_add_u32_e32 v1, 16, v0
	v_cmp_gt_u32_e32 vcc, 0x1000, v0
	v_add_u32_e32 v2, 0xffffe000, v0
	s_nop 0
	v_cndmask_b32_e32 v1, v1, v0, vcc
	v_cmp_gt_u32_e32 vcc, 0x3000, v0
	s_nop 1
	v_cndmask_b32_e32 v1, v2, v1, vcc
	v_cmp_gt_u32_e32 vcc, 0x3010, v0
	s_nop 1
	v_cndmask_b32_e32 v1, -1, v1, vcc
	v_cndmask_b32_e64 v1, v0, v1, s[34:35]
	v_lshl_add_u32 v136, v1, 2, v4
	v_lshl_add_u64 v[2:3], s[28:29], 0, v[136:137]
	v_cmp_le_i32_e32 vcc, 0, v1
	v_mov_b32_e32 v56, 0
	v_mov_b32_e32 v57, 0
	v_mov_b32_e32 v58, 0
	v_mov_b32_e32 v59, 0
	v_mov_b32_e32 v60, 0
	v_mov_b32_e32 v61, 0
	v_mov_b32_e32 v62, 0
	v_mov_b32_e32 v63, 0
	s_and_saveexec_b64 s[44:45], vcc
	global_load_dword v56, v[2:3], off
	v_lshl_add_u64 v[2:3], v[2:3], 0, s[42:43]
	global_load_dword v57, v[2:3], off
	v_lshl_add_u64 v[2:3], v[2:3], 0, s[42:43]
	global_load_dword v58, v[2:3], off
	v_lshl_add_u64 v[2:3], v[2:3], 0, s[42:43]
	global_load_dword v59, v[2:3], off
	v_lshl_add_u64 v[2:3], v[2:3], 0, s[42:43]
	global_load_dword v60, v[2:3], off
	v_lshl_add_u64 v[2:3], v[2:3], 0, s[42:43]
	global_load_dword v61, v[2:3], off
	v_lshl_add_u64 v[2:3], v[2:3], 0, s[42:43]
	global_load_dword v62, v[2:3], off
	v_lshl_add_u64 v[2:3], v[2:3], 0, s[42:43]
	global_load_dword v63, v[2:3], off
	s_mov_b64 exec, s[44:45]
	s_lshl_b32 s40, s41, 12
	v_add_u32_e32 v136, s40, v46
	v_lshl_add_u64 v[114:115], s[30:31], 0, v[136:137]
	s_add_i32 s41, s41, 64
	v_add_u32_e32 v0, s41, v40
	v_add_u32_e32 v1, 16, v0
	v_cmp_gt_u32_e32 vcc, 0x1000, v0
	v_add_u32_e32 v2, 0xffffe000, v0
	s_nop 0
	v_cndmask_b32_e32 v1, v1, v0, vcc
	v_cmp_gt_u32_e32 vcc, 0x3000, v0
	s_nop 1
	v_cndmask_b32_e32 v1, v2, v1, vcc
	v_cmp_gt_u32_e32 vcc, 0x3010, v0
	s_nop 1
	v_cndmask_b32_e32 v1, -1, v1, vcc
	v_cndmask_b32_e64 v1, v0, v1, s[34:35]
	v_lshl_add_u32 v136, v1, 2, v4
	v_lshl_add_u64 v[2:3], s[28:29], 0, v[136:137]
; #define LDS_BARRIER() do { asm volatile("s_waitcnt lgkmcnt(0)" ::: "memory"); __builtin_amdgcn_s_barrier(); asm volatile("" ::: "memory"); } while (0)
; __device__ __forceinline__ u32x4 pack8(const float* v) { u32x4 o; o[0] = pk2(v[0], v[1]); o[1] = pk2(v[2], v[3]); o[2] = pk2(v[4], v[5]); o[3] = pk2(v[6], v[7]); return o; }
; __device__ __forceinline__ void tr_tile(const int tid, float* tile, const float* src, int ld, int k0, int j0, bool remap, bf16_t* dst, int ldd, int kd0) {
;     const int jj = tid & 63, kq = tid >> 6;
;     const int col = remap ? win_col(j0 + jj) : (j0 + jj);
; #pragma unroll
;     for (int i = 0; i < 8; ++i) { const int kk = kq + 8 * i; tile[kk * 65 + jj] = col >= 0 ? src[(size_t)(k0 + kk) * ld + col] : 0.f; }
;     LDS_BARRIER();
;     const int j = tid >> 3, pc = tid & 7; float v[8];
; #pragma unroll
;     for (int e = 0; e < 8; ++e) v[e] = tile[(pc * 8 + e) * 65 + j];
;     *(u32x4*)(dst + (size_t)(j0 + j) * ldd + kd0 + pc * 8) = pack8(v);
;     LDS_BARRIER();
; }
	v_cmp_le_i32_e32 vcc, 0, v1
	v_mov_b32_e32 v64, 0
	v_mov_b32_e32 v65, 0
	v_mov_b32_e32 v66, 0
	v_mov_b32_e32 v67, 0
	v_mov_b32_e32 v68, 0
	v_mov_b32_e32 v69, 0
	v_mov_b32_e32 v70, 0
	v_mov_b32_e32 v71, 0
	s_and_saveexec_b64 s[44:45], vcc
	global_load_dword v64, v[2:3], off
	v_lshl_add_u64 v[2:3], v[2:3], 0, s[42:43]
	global_load_dword v65, v[2:3], off
	v_lshl_add_u64 v[2:3], v[2:3], 0, s[42:43]
	global_load_dword v66, v[2:3], off
	v_lshl_add_u64 v[2:3], v[2:3], 0, s[42:43]
	global_load_dword v67, v[2:3], off
	v_lshl_add_u64 v[2:3], v[2:3], 0, s[42:43]
	global_load_dword v68, v[2:3], off
	v_lshl_add_u64 v[2:3], v[2:3], 0, s[42:43]
	global_load_dword v69, v[2:3], off
	v_lshl_add_u64 v[2:3], v[2:3], 0, s[42:43]
	global_load_dword v70, v[2:3], off
	v_lshl_add_u64 v[2:3], v[2:3], 0, s[42:43]
	global_load_dword v71, v[2:3], off
	s_mov_b64 exec, s[44:45]
	s_lshl_b32 s40, s41, 12
	v_add_u32_e32 v136, s40, v46
	v_lshl_add_u64 v[116:117], s[30:31], 0, v[136:137]
	s_add_i32 s41, s41, 64
	v_add_u32_e32 v0, s41, v40
	v_add_u32_e32 v1, 16, v0
	v_cmp_gt_u32_e32 vcc, 0x1000, v0
	v_add_u32_e32 v2, 0xffffe000, v0
	s_nop 0
	v_cndmask_b32_e32 v1, v1, v0, vcc
	v_cmp_gt_u32_e32 vcc, 0x3000, v0
	s_nop 1
	v_cndmask_b32_e32 v1, v2, v1, vcc
	v_cmp_gt_u32_e32 vcc, 0x3010, v0
	s_nop 1
	v_cndmask_b32_e32 v1, -1, v1, vcc
	v_cndmask_b32_e64 v1, v0, v1, s[34:35]
	v_lshl_add_u32 v136, v1, 2, v4
	v_lshl_add_u64 v[2:3], s[28:29], 0, v[136:137]
	v_cmp_le_i32_e32 vcc, 0, v1
	v_mov_b32_e32 v72, 0
	v_mov_b32_e32 v73, 0
	v_mov_b32_e32 v74, 0
	v_mov_b32_e32 v75, 0
	v_mov_b32_e32 v76, 0
	v_mov_b32_e32 v77, 0
	v_mov_b32_e32 v78, 0
	v_mov_b32_e32 v79, 0
	s_and_saveexec_b64 s[44:45], vcc
	global_load_dword v72, v[2:3], off
	v_lshl_add_u64 v[2:3], v[2:3], 0, s[42:43]
	global_load_dword v73, v[2:3], off
	v_lshl_add_u64 v[2:3], v[2:3], 0, s[42:43]
	global_load_dword v74, v[2:3], off
	v_lshl_add_u64 v[2:3], v[2:3], 0, s[42:43]
	global_load_dword v75, v[2:3], off
	v_lshl_add_u64 v[2:3], v[2:3], 0, s[42:43]
	global_load_dword v76, v[2:3], off
	v_lshl_add_u64 v[2:3], v[2:3], 0, s[42:43]
	global_load_dword v77, v[2:3], off
	v_lshl_add_u64 v[2:3], v[2:3], 0, s[42:43]
	global_load_dword v78, v[2:3], off
	v_lshl_add_u64 v[2:3], v[2:3], 0, s[42:43]
	global_load_dword v79, v[2:3], off
	s_mov_b64 exec, s[44:45]
	s_lshl_b32 s40, s41, 12
	v_add_u32_e32 v136, s40, v46
	v_lshl_add_u64 v[118:119], s[30:31], 0, v[136:137]
	s_add_i32 s41, s41, 64
	s_waitcnt vmcnt(0)
	ds_write_b32 v44, v48
	ds_write_b32 v44, v49 offset:2080
	ds_write_b32 v44, v50 offset:4160
	ds_write_b32 v44, v51 offset:6240
	ds_write_b32 v44, v52 offset:8320
	ds_write_b32 v44, v53 offset:10400
	ds_write_b32 v44, v54 offset:12480
	ds_write_b32 v44, v55 offset:14560
	ds_write_b32 v44, v56 offset:16640
	ds_write_b32 v44, v57 offset:18720
	ds_write_b32 v44, v58 offset:20800
	ds_write_b32 v44, v59 offset:22880
	ds_write_b32 v44, v60 offset:24960
	ds_write_b32 v44, v61 offset:27040
	ds_write_b32 v44, v62 offset:29120
	ds_write_b32 v44, v63 offset:31200
	ds_write_b32 v44, v64 offset:33280
	ds_write_b32 v44, v65 offset:35360
	ds_write_b32 v44, v66 offset:37440
	ds_write_b32 v44, v67 offset:39520
	ds_write_b32 v44, v68 offset:41600
	ds_write_b32 v44, v69 offset:43680
	ds_write_b32 v44, v70 offset:45760
	ds_write_b32 v44, v71 offset:47840
	ds_write_b32 v44, v72 offset:49920
	ds_write_b32 v44, v73 offset:52000
	ds_write_b32 v44, v74 offset:54080
	ds_write_b32 v44, v75 offset:56160
	ds_write_b32 v44, v76 offset:58240
	ds_write_b32 v44, v77 offset:60320
	ds_write_b32 v44, v78 offset:62400
	ds_write_b32 v44, v79 offset:64480
	s_waitcnt lgkmcnt(0)
	s_barrier
	ds_read2_b32 v[48:49], v144 offset1:65
	ds_read2_b32 v[50:51], v144 offset0:130 offset1:195
	ds_read2_b32 v[52:53], v145 offset0:4 offset1:69
	ds_read2_b32 v[54:55], v145 offset0:134 offset1:199
	ds_read2_b32 v[56:57], v146 offset1:65
	ds_read2_b32 v[58:59], v146 offset0:130 offset1:195
	ds_read2_b32 v[60:61], v147 offset0:4 offset1:69
	ds_read2_b32 v[62:63], v147 offset0:134 offset1:199
	ds_read2_b32 v[64:65], v148 offset1:65
	ds_read2_b32 v[66:67], v148 offset0:130 offset1:195
	ds_read2_b32 v[68:69], v149 offset0:4 offset1:69
	ds_read2_b32 v[70:71], v149 offset0:134 offset1:199
	ds_read2_b32 v[72:73], v150 offset1:65
	ds_read2_b32 v[74:75], v150 offset0:130 offset1:195
	ds_read2_b32 v[76:77], v151 offset0:4 offset1:69
	ds_read2_b32 v[78:79], v151 offset0:134 offset1:199
	s_waitcnt lgkmcnt(12)
	v_cvt_pk_bf16_f32 v48, v48, v49
	v_cvt_pk_bf16_f32 v49, v50, v51
	v_cvt_pk_bf16_f32 v50, v52, v53
	v_cvt_pk_bf16_f32 v51, v54, v55
	global_store_dwordx4 v[112:113], v[48:51], off
	s_waitcnt lgkmcnt(8)
	v_cvt_pk_bf16_f32 v56, v56, v57
	v_cvt_pk_bf16_f32 v57, v58, v59
	v_cvt_pk_bf16_f32 v58, v60, v61
	v_cvt_pk_bf16_f32 v59, v62, v63
	global_store_dwordx4 v[114:115], v[56:59], off
	s_waitcnt lgkmcnt(4)
	v_cvt_pk_bf16_f32 v64, v64, v65
	v_cvt_pk_bf16_f32 v65, v66, v67
	v_cvt_pk_bf16_f32 v66, v68, v69
	v_cvt_pk_bf16_f32 v67, v70, v71
	global_store_dwordx4 v[116:117], v[64:67], off
	s_waitcnt lgkmcnt(0)
	v_cvt_pk_bf16_f32 v72, v72, v73
	v_cvt_pk_bf16_f32 v73, v74, v75
	v_cvt_pk_bf16_f32 v74, v76, v77
	v_cvt_pk_bf16_f32 v75, v78, v79
	global_store_dwordx4 v[118:119], v[72:75], off
	s_barrier
	s_add_i32 s21, s21, s80
	s_cmpk_gt_i32 s21, 0x81f
	s_cbranch_scc0 .Lcv_loop
	s_branch .LBB0_831
